# retention units: off-diagonal tiles use factored decay weights (per-lane x per-register constants) instead of 32 exps and index math per tile
# speedup vs baseline: 1.0141x; 1.0042x over previous
.LBB0_1183:
	s_waitcnt vmcnt(1)
	v_mul_f32_e32 v0, 0xbfb8aa3b, v2
	v_rndne_f32_e32 v3, v0
	s_mov_b32 s12, 0xbfb8aa3b
	v_sub_f32_e32 v4, v0, v3
	v_fma_f32 v0, v2, s12, -v0
	v_fmac_f32_e32 v0, 0xb2a5705f, v2
	v_add_f32_e32 v0, v4, v0
	v_exp_f32_e32 v0, v0
	v_cvt_i32_f32_e32 v3, v3
	s_mov_b32 s14, 0x42ce8ed0
	v_cmp_nlt_f32_e32 vcc, s14, v2
	s_mov_b32 s24, 0xc2b17218
	v_ldexp_f32 v3, v0, v3
	v_cndmask_b32_e32 v3, 0, v3, vcc
	v_cmp_ngt_f32_e32 vcc, s24, v2
	s_mov_b32 s13, 0x3f2aaaab
	s_mov_b32 s15, 0x3f317218
	v_cndmask_b32_e32 v4, v172, v3, vcc
	v_add_f32_e32 v5, 1.0, v4
	v_add_f32_e32 v2, -1.0, v5
	v_sub_f32_e32 v3, v2, v5
	v_add_f32_e32 v3, 1.0, v3
	v_sub_f32_e32 v2, v4, v2
	v_add_f32_e32 v6, v2, v3
	v_frexp_mant_f32_e32 v7, v5
	v_cvt_f64_f32_e32 v[2:3], v5
	v_frexp_exp_i32_f64_e32 v2, v[2:3]
	v_cmp_gt_f32_e32 vcc, s13, v7
	s_mov_b32 s21, 0x7f800000
	s_mov_b32 s25, 0x33800000
	v_subbrev_co_u32_e32 v2, vcc, 0, v2, vcc
	v_sub_u32_e32 v3, 0, v2
	v_ldexp_f32 v5, v5, v3
	v_ldexp_f32 v3, v6, v3
	v_add_f32_e32 v6, -1.0, v5
	v_add_f32_e32 v9, 1.0, v5
	v_add_f32_e32 v7, 1.0, v6
	v_add_f32_e32 v10, -1.0, v9
	v_sub_f32_e32 v7, v5, v7
	v_sub_f32_e32 v5, v5, v10
	v_add_f32_e32 v7, v3, v7
	v_add_f32_e32 v3, v3, v5
	v_add_f32_e32 v5, v9, v3
	v_rcp_f32_e32 v10, v5
	v_add_f32_e32 v8, v6, v7
	v_sub_f32_e32 v6, v6, v8
	v_add_f32_e32 v6, v7, v6
	v_sub_f32_e32 v7, v9, v5
	v_add_f32_e32 v3, v3, v7
	v_mul_f32_e32 v7, v8, v10
	v_mul_f32_e32 v9, v5, v7
	v_fma_f32 v11, v7, v5, -v9
	v_fmac_f32_e32 v11, v7, v3
	v_add_f32_e32 v12, v9, v11
	v_sub_f32_e32 v13, v8, v12
	v_sub_f32_e32 v8, v8, v13
	v_sub_f32_e32 v9, v12, v9
	v_sub_f32_e32 v8, v8, v12
	v_add_f32_e32 v6, v6, v8
	v_sub_f32_e32 v8, v9, v11
	v_add_f32_e32 v6, v8, v6
	v_add_f32_e32 v8, v13, v6
	v_mul_f32_e32 v9, v10, v8
	v_mul_f32_e32 v11, v5, v9
	v_fma_f32 v5, v9, v5, -v11
	v_fmac_f32_e32 v5, v9, v3
	v_sub_f32_e32 v3, v13, v8
	v_add_f32_e32 v3, v6, v3
	v_add_f32_e32 v6, v11, v5
	v_sub_f32_e32 v12, v8, v6
	v_sub_f32_e32 v8, v8, v12
	v_sub_f32_e32 v11, v6, v11
	v_sub_f32_e32 v6, v8, v6
	v_add_f32_e32 v3, v3, v6
	v_sub_f32_e32 v5, v11, v5
	v_cvt_f32_i32_e32 v2, v2
	v_add_f32_e32 v3, v5, v3
	v_add_f32_e32 v5, v7, v9
	v_add_f32_e32 v3, v12, v3
	v_sub_f32_e32 v6, v5, v7
	v_mul_f32_e32 v3, v10, v3
	v_sub_f32_e32 v6, v9, v6
	v_add_f32_e32 v3, v6, v3
	v_mul_f32_e32 v9, 0x3f317218, v2
	v_add_f32_e32 v6, v5, v3
	v_fma_f32 v10, v2, s15, -v9
	v_mul_f32_e32 v7, v6, v6
	v_fmac_f32_e32 v10, 0xb102e308, v2
	v_sub_f32_e32 v2, v6, v5
	v_fmamk_f32 v8, v7, 0x3e9b6dac, v168
	v_sub_f32_e32 v2, v3, v2
	v_add_f32_e32 v3, v9, v10
	v_fmaak_f32 v8, v7, v8, 0x3f2aaada
	v_sub_f32_e32 v5, v3, v9
	v_ldexp_f32 v9, v6, 1
	v_mul_f32_e32 v6, v6, v7
	v_mul_f32_e32 v6, v6, v8
	v_add_f32_e32 v7, v9, v6
	v_sub_f32_e32 v8, v7, v9
	v_ldexp_f32 v2, v2, 1
	v_sub_f32_e32 v6, v6, v8
	v_add_f32_e32 v2, v2, v6
	v_add_f32_e32 v6, v7, v2
	v_sub_f32_e32 v7, v6, v7
	v_sub_f32_e32 v2, v2, v7
	v_add_f32_e32 v7, v3, v6
	v_sub_f32_e32 v8, v7, v3
	v_sub_f32_e32 v9, v7, v8
	v_sub_f32_e32 v5, v10, v5
	v_sub_f32_e32 v3, v3, v9
	v_sub_f32_e32 v6, v6, v8
	v_add_f32_e32 v3, v6, v3
	v_add_f32_e32 v6, v5, v2
	v_sub_f32_e32 v8, v6, v5
	v_sub_f32_e32 v9, v6, v8
	v_sub_f32_e32 v5, v5, v9
	v_sub_f32_e32 v2, v2, v8
	v_add_f32_e32 v3, v6, v3
	v_add_f32_e32 v2, v2, v5
	v_add_f32_e32 v5, v7, v3
	v_sub_f32_e32 v6, v5, v7
	v_sub_f32_e32 v3, v3, v6
	v_add_f32_e32 v2, v2, v3
	s_waitcnt vmcnt(0)
	v_mul_f32_e32 v3, 0xbfb8aa3b, v1
	v_add_f32_e32 v2, v5, v2
	v_rndne_f32_e32 v5, v3
	v_sub_f32_e32 v6, v3, v5
	v_fma_f32 v3, v1, s12, -v3
	v_fmac_f32_e32 v3, 0xb2a5705f, v1
	v_add_f32_e32 v3, v6, v3
	v_exp_f32_e32 v3, v3
	v_cvt_i32_f32_e32 v5, v5
	v_cmp_neq_f32_e32 vcc, s21, v4
	s_lshl_b32 s26, s1, 8
	s_mul_i32 s1, s1, 0x160000
	v_cndmask_b32_e32 v2, v172, v2, vcc
	v_cmp_lt_f32_e64 vcc, |v4|, s25
	v_readlane_b32 s8, v254, 62
	s_mul_hi_u32 s0, s26, 0x1600
	v_cndmask_b32_e32 v2, v2, v4, vcc
	v_mul_f32_e32 v115, 0xbfb8aa3b, v2
	v_ldexp_f32 v2, v3, v5
	v_cmp_nlt_f32_e32 vcc, s14, v1
	v_readlane_b32 s9, v254, 63
	s_add_u32 s7, s8, s1
	v_cndmask_b32_e32 v2, 0, v2, vcc
	v_cmp_ngt_f32_e32 vcc, s24, v1
	s_addc_u32 s8, s9, s0
	s_lshl_b32 s19, s6, 6
	v_cndmask_b32_e32 v1, v172, v2, vcc
	v_add_f32_e32 v4, 1.0, v1
	v_add_f32_e32 v2, -1.0, v4
	v_sub_f32_e32 v3, v2, v4
	v_add_f32_e32 v3, 1.0, v3
	v_sub_f32_e32 v2, v1, v2
	v_add_f32_e32 v5, v2, v3
	v_frexp_mant_f32_e32 v6, v4
	v_cvt_f64_f32_e32 v[2:3], v4
	v_frexp_exp_i32_f64_e32 v2, v[2:3]
	v_cmp_gt_f32_e32 vcc, s13, v6
	s_lshl_b32 s3, s6, 7
	s_add_u32 s16, s7, s3
	v_subbrev_co_u32_e32 v10, vcc, 0, v2, vcc
	v_sub_u32_e32 v2, 0, v10
	v_ldexp_f32 v3, v4, v2
	v_add_f32_e32 v4, -1.0, v3
	v_add_f32_e32 v7, 1.0, v3
	v_ldexp_f32 v2, v5, v2
	v_add_f32_e32 v5, 1.0, v4
	v_add_f32_e32 v8, -1.0, v7
	v_sub_f32_e32 v5, v3, v5
	v_sub_f32_e32 v3, v3, v8
	v_add_f32_e32 v5, v2, v5
	v_add_f32_e32 v2, v2, v3
	v_add_f32_e32 v11, v7, v2
	v_rcp_f32_e32 v12, v11
	v_add_f32_e32 v6, v4, v5
	v_sub_f32_e32 v4, v4, v6
	v_add_f32_e32 v3, v5, v4
	v_sub_f32_e32 v4, v7, v11
	v_mul_f32_e32 v14, v6, v12
	v_add_f32_e32 v13, v2, v4
	v_mul_f32_e32 v2, v11, v14
	v_fma_f32 v4, v14, v11, -v2
	v_fmac_f32_e32 v4, v14, v13
	s_addc_u32 s17, s8, 0
	s_mul_i32 s6, s6, 0x500000
	v_readlane_b32 s8, v255, 33
	v_add_f32_e32 v5, v2, v4
	s_add_u32 s10, s8, s6
	v_readlane_b32 s8, v255, 34
	v_sub_f32_e32 v15, v6, v5
	s_addc_u32 s11, s8, 0
	s_lshl_b64 s[8:9], s[26:27], 1
	v_sub_f32_e32 v6, v6, v15
	v_mov_b32_e32 v19, v128
	s_add_u32 s10, s10, s8
	v_sub_f32_e32 v2, v5, v2
	v_sub_f32_e32 v5, v6, v5
	s_addc_u32 s11, s11, s9
	v_readfirstlane_b32 s12, v19
	v_add_f32_e32 v3, v3, v5
	v_sub_f32_e32 v2, v2, v4
	s_ashr_i32 s12, s12, 1
	v_add_f32_e32 v16, v2, v3
	v_mov_b32_e32 v2, s12
	s_movk_i32 s12, 0xffe0
	v_lshlrev_b32_e32 v22, 3, v19
	v_bfe_u32 v20, v19, 5, 1
	v_bfi_b32 v116, s12, v2, v19
	v_mov_b64_e32 v[2:3], s[16:17]
	s_movk_i32 s14, 0x1600
	v_ashrrev_i32_e32 v21, 3, v19
	v_and_b32_e32 v23, 56, v22
	v_mad_i64_i32 v[112:113], s[12:13], v116, s14, v[2:3]
	v_lshlrev_b32_e32 v130, 4, v20
	v_mad_i64_i32 v[2:3], s[12:13], v21, s14, v[2:3]
	v_lshlrev_b32_e32 v6, 1, v23
	v_mov_b32_e32 v7, v131
	v_lshl_add_u64 v[4:5], v[112:113], 0, v[130:131]
	v_lshl_add_u64 v[2:3], v[2:3], 0, v[6:7]
	v_mov_b64_e32 v[8:9], s[10:11]
	s_mov_b32 s12, 0x14000
	global_load_dwordx4 v[108:111], v[4:5], off
	global_load_dwordx4 v[104:107], v[4:5], off offset:32
	global_load_dwordx4 v[100:103], v[4:5], off offset:64
	global_load_dwordx4 v[96:99], v[4:5], off offset:96
	s_barrier
	global_load_dwordx4 v[2:5], v[2:3], off offset:1024
	v_mad_i64_i32 v[8:9], s[10:11], v21, s12, v[8:9]
	v_lshl_add_u64 v[6:7], v[8:9], 0, v[6:7]
	global_load_dwordx4 v[6:9], v[6:7], off
	v_add_f32_e32 v17, v15, v16
	v_mul_f32_e32 v18, v12, v17
	v_mul_f32_e32 v24, v11, v18
	v_fma_f32 v11, v18, v11, -v24
	v_fmac_f32_e32 v11, v18, v13
	v_sub_f32_e32 v13, v15, v17
	v_add_f32_e32 v15, v24, v11
	v_add_f32_e32 v13, v16, v13
	v_sub_f32_e32 v16, v15, v24
	v_sub_f32_e32 v24, v17, v15
	v_sub_f32_e32 v17, v17, v24
	v_sub_f32_e32 v15, v17, v15
	v_add_f32_e32 v13, v13, v15
	v_sub_f32_e32 v11, v16, v11
	v_add_f32_e32 v11, v11, v13
	v_add_f32_e32 v11, v24, v11
	v_cvt_f32_i32_e32 v10, v10
	v_mul_f32_e32 v11, v12, v11
	v_add_f32_e32 v12, v14, v18
	v_sub_f32_e32 v13, v12, v14
	v_sub_f32_e32 v13, v18, v13
	v_add_f32_e32 v11, v13, v11
	v_mul_f32_e32 v16, 0x3f317218, v10
	v_add_f32_e32 v13, v12, v11
	v_fma_f32 v17, v10, s15, -v16
	v_mul_f32_e32 v14, v13, v13
	v_fmac_f32_e32 v17, 0xb102e308, v10
	v_sub_f32_e32 v10, v13, v12
	v_fmamk_f32 v15, v14, 0x3e9b6dac, v168
	v_sub_f32_e32 v10, v11, v10
	v_add_f32_e32 v11, v16, v17
	v_fmaak_f32 v15, v14, v15, 0x3f2aaada
	v_sub_f32_e32 v12, v11, v16
	v_ldexp_f32 v16, v13, 1
	v_mul_f32_e32 v13, v13, v14
	v_mul_f32_e32 v13, v13, v15
	v_add_f32_e32 v14, v16, v13
	v_sub_f32_e32 v15, v14, v16
	v_ldexp_f32 v10, v10, 1
	v_sub_f32_e32 v13, v13, v15
	v_add_f32_e32 v10, v10, v13
	v_add_f32_e32 v13, v14, v10
	v_sub_f32_e32 v14, v13, v14
	v_sub_f32_e32 v10, v10, v14
	v_add_f32_e32 v14, v11, v13
	v_sub_f32_e32 v15, v14, v11
	v_sub_f32_e32 v16, v14, v15
	v_sub_f32_e32 v12, v17, v12
	v_sub_f32_e32 v11, v11, v16
	v_sub_f32_e32 v13, v13, v15
	v_add_f32_e32 v11, v13, v11
	v_add_f32_e32 v13, v12, v10
	v_sub_f32_e32 v15, v13, v12
	v_sub_f32_e32 v16, v13, v15
	v_sub_f32_e32 v12, v12, v16
	v_sub_f32_e32 v10, v10, v15
	v_add_f32_e32 v11, v13, v11
	v_add_f32_e32 v10, v10, v12
	v_add_f32_e32 v12, v14, v11
	v_sub_f32_e32 v13, v12, v14
	v_sub_f32_e32 v11, v11, v13
	v_add_f32_e32 v10, v10, v11
	v_add_f32_e32 v10, v12, v10
	v_cmp_neq_f32_e32 vcc, s21, v1
	s_movk_i32 s10, 0x48
	s_mov_b32 s7, s27
	v_cndmask_b32_e32 v10, v172, v10, vcc
	v_cmp_lt_f32_e64 vcc, |v1|, s25
	v_and_b32_e32 v73, 31, v19
	v_lshlrev_b32_e32 v72, 3, v20
	v_cndmask_b32_e32 v1, v10, v1, vcc
	v_mul_f32_e32 v117, 0xbfb8aa3b, v1
	v_mul_lo_u32 v1, v21, s10
	v_and_b32_e32 v10, 48, v22
	v_add_lshl_u32 v79, v1, v23, 1
	v_add_u32_e32 v1, v1, v10
	v_lshlrev_b32_e32 v10, 2, v19
	v_and_or_b32 v1, v10, 4, v1
	v_lshlrev_b32_e32 v80, 1, v1
	v_add_u32_e32 v1, 0, v79
	s_waitcnt vmcnt(1)
	ds_write_b128 v1, v[2:5]
	v_add_u32_e32 v1, 0, v80
	v_add_u32_e32 v1, 0x2000, v1
	v_mov_b64_e32 v[2:3], s[6:7]
	s_waitcnt vmcnt(0)
	ds_write2_b64 v1, v[6:7], v[8:9] offset0:128 offset1:130
	v_mul_u32_u24_e32 v1, 0x48, v73
	v_mad_i64_i32 v[2:3], s[6:7], v21, s12, v[2:3]
	v_add_lshl_u32 v81, v72, v1, 1
	v_lshlrev_b32_e32 v1, 4, v19
	v_readlane_b32 s6, v253, 8
	v_and_b32_e32 v1, 0x70, v1
	s_add_u32 s6, s6, s8
	v_readlane_b32 s7, v253, 9
	v_or_b32_e32 v2, v2, v1
	s_addc_u32 s7, s7, s9
	s_or_b32 s1, s1, s3
	v_lshl_add_u64 v[74:75], s[6:7], 0, v[2:3]
	v_mov_b32_e32 v2, s1
	v_mov_b32_e32 v3, s0
	v_mad_i64_i32 v[2:3], s[0:1], v21, s14, v[2:3]
	v_readlane_b32 s0, v253, 10
	v_mov_b32_e32 v0, 0
	v_lshlrev_b32_e32 v114, 2, v20
	v_or_b32_e32 v2, v2, v1
	v_readlane_b32 s1, v253, 11
	s_mov_b32 s20, 0
	v_mul_u32_u24_e32 v78, 0x90, v73
	v_sub_u32_e32 v82, v116, v114
	v_lshl_add_u64 v[76:77], s[0:1], 0, v[2:3]
	s_mov_b32 s6, 0
	v_mov_b32_e32 v1, v0
	v_mov_b32_e32 v2, v0
	v_mov_b32_e32 v3, v0
	v_mov_b32_e32 v4, v0
	v_mov_b32_e32 v5, v0
	v_mov_b32_e32 v6, v0
	v_mov_b32_e32 v7, v0
	v_mov_b32_e32 v8, v0
	v_mov_b32_e32 v9, v0
	v_mov_b32_e32 v10, v0
	v_mov_b32_e32 v11, v0
	v_mov_b32_e32 v12, v0
	v_mov_b32_e32 v13, v0
	v_mov_b32_e32 v14, v0
	v_mov_b32_e32 v15, v0
	v_mov_b32_e32 v16, v0
	v_mov_b32_e32 v17, v0
	v_mov_b32_e32 v18, v0
	v_mov_b32_e32 v19, v0
	v_mov_b32_e32 v20, v0
	v_mov_b32_e32 v21, v0
	v_mov_b32_e32 v22, v0
	v_mov_b32_e32 v23, v0
	v_mov_b32_e32 v24, v0
	v_mov_b32_e32 v25, v0
	v_mov_b32_e32 v26, v0
	v_mov_b32_e32 v27, v0
	v_mov_b32_e32 v28, v0
	v_mov_b32_e32 v29, v0
	v_mov_b32_e32 v30, v0
	v_mov_b32_e32 v31, v0
	s_mov_b64 s[8:9], 0x58000
	v_mul_f32_e32 v214, 0x42600000, v115
	v_mul_f32_e32 v215, 0x42400000, v115
	v_mul_f32_e32 v216, 0x42200000, v115
	v_mul_f32_e32 v217, 0x42000000, v115
	v_exp_f32_e32 v214, v214
	v_exp_f32_e32 v215, v215
	v_exp_f32_e32 v216, v216
	v_exp_f32_e32 v217, v217
	s_nop 0
	v_readfirstlane_b32 s70, v214
	v_readfirstlane_b32 s71, v215
	v_readfirstlane_b32 s72, v216
	v_readfirstlane_b32 s73, v217
	v_mul_f32_e32 v214, 0x41c00000, v115
	v_mul_f32_e32 v215, 0x41800000, v115
	v_mul_f32_e32 v216, 0x41000000, v115
	v_mul_f32_e32 v217, 0x00000000, v115
	v_exp_f32_e32 v214, v214
	v_exp_f32_e32 v215, v215
	v_exp_f32_e32 v216, v216
	v_exp_f32_e32 v217, v217
	s_nop 0
	v_readfirstlane_b32 s74, v214
	v_readfirstlane_b32 s75, v215
	v_readfirstlane_b32 s76, v216
	v_readfirstlane_b32 s77, v217
	v_mul_f32_e32 v214, 0x40400000, v115
	v_mul_f32_e32 v215, 0x40000000, v115
	v_mul_f32_e32 v216, 0x3f800000, v115
	v_mul_f32_e32 v217, 0x00000000, v115
	v_exp_f32_e32 v214, v214
	v_exp_f32_e32 v215, v215
	v_exp_f32_e32 v216, v216
	v_exp_f32_e32 v217, v217
	s_nop 0
	v_readfirstlane_b32 s78, v214
	v_readfirstlane_b32 s79, v215
	v_readfirstlane_b32 s80, v216
	v_readfirstlane_b32 s81, v217
	v_mul_f32_e32 v214, 0x00000000, v117
	v_mul_f32_e32 v215, 0x41000000, v117
	v_mul_f32_e32 v216, 0x41800000, v117
	v_mul_f32_e32 v217, 0x41c00000, v117
	v_exp_f32_e32 v214, v214
	v_exp_f32_e32 v215, v215
	v_exp_f32_e32 v216, v216
	v_exp_f32_e32 v217, v217
	s_nop 0
	v_readfirstlane_b32 s82, v214
	v_readfirstlane_b32 s83, v215
	v_readfirstlane_b32 s84, v216
	v_readfirstlane_b32 s85, v217
	v_mul_f32_e32 v214, 0x42000000, v117
	v_mul_f32_e32 v215, 0x42200000, v117
	v_mul_f32_e32 v216, 0x42400000, v117
	v_mul_f32_e32 v217, 0x42600000, v117
	v_exp_f32_e32 v214, v214
	v_exp_f32_e32 v215, v215
	v_exp_f32_e32 v216, v216
	v_exp_f32_e32 v217, v217
	s_nop 0
	v_readfirstlane_b32 s86, v214
	v_readfirstlane_b32 s87, v215
	v_readfirstlane_b32 s88, v216
	v_readfirstlane_b32 s89, v217
	v_mul_f32_e32 v214, 0x00000000, v117
	v_mul_f32_e32 v215, 0x3f800000, v117
	v_mul_f32_e32 v216, 0x40000000, v117
	v_mul_f32_e32 v217, 0x40400000, v117
	v_exp_f32_e32 v214, v214
	v_exp_f32_e32 v215, v215
	v_exp_f32_e32 v216, v216
	v_exp_f32_e32 v217, v217
	s_nop 0
	v_readfirstlane_b32 s90, v214
	v_readfirstlane_b32 s91, v215
	v_readfirstlane_b32 s92, v216
	v_readfirstlane_b32 s93, v217
	v_readfirstlane_b32 s94, v82
	s_waitcnt lgkmcnt(0)
	s_barrier
	s_branch .LBB0_1184
.Lret_lean_f:
	s_and_b32 s0, s6, 1
	s_mul_i32 s1, s0, 0x4800
	v_add_u32_e32 v223, s1, v81
	global_load_dwordx4 v[68:71], v[76:77], off
	global_load_dwordx4 v[64:67], v[74:75], off
	ds_read_b128 v[182:185], v223
	ds_read_b128 v[186:189], v223 offset:32
	ds_read_b128 v[190:193], v223 offset:64
	ds_read_b128 v[194:197], v223 offset:96
	ds_read_b128 v[198:201], v223 offset:4608
	ds_read_b128 v[202:205], v223 offset:4640
	ds_read_b128 v[206:209], v223 offset:4672
	ds_read_b128 v[210:213], v223 offset:4704
	s_xor_b32 s0, s0, 1
	s_mulk_i32 s0, 0x4800
	s_add_i32 s6, s6, 1
	v_lshl_add_u64 v[74:75], v[74:75], 0, s[30:31]
	v_lshl_add_u64 v[76:77], v[76:77], 0, s[8:9]
	v_add_u32_e32 v214, s20, v82
	v_add_u32_e32 v214, 0xffffffc5, v214
	v_cvt_f32_i32_e32 v214, v214
	v_mul_f32_e32 v214, v115, v214
	v_exp_f32_e32 v214, v214
	s_waitcnt lgkmcnt(7)
	v_mfma_f32_32x32x16_bf16 v[48:63], v[182:185], v[108:111], 0
	s_waitcnt lgkmcnt(6)
	v_mfma_f32_32x32x16_bf16 v[48:63], v[186:189], v[104:107], v[48:63]
	s_waitcnt lgkmcnt(5)
	v_mfma_f32_32x32x16_bf16 v[48:63], v[190:193], v[100:103], v[48:63]
	s_waitcnt lgkmcnt(4)
	v_mfma_f32_32x32x16_bf16 v[48:63], v[194:197], v[96:99], v[48:63]
	s_waitcnt lgkmcnt(3)
	v_mfma_f32_32x32x16_bf16 v[32:47], v[198:201], v[108:111], 0
	s_waitcnt lgkmcnt(2)
	v_mfma_f32_32x32x16_bf16 v[32:47], v[202:205], v[104:107], v[32:47]
	s_waitcnt lgkmcnt(1)
	v_mfma_f32_32x32x16_bf16 v[32:47], v[206:209], v[100:103], v[32:47]
	s_waitcnt lgkmcnt(0)
	v_mfma_f32_32x32x16_bf16 v[32:47], v[210:213], v[96:99], v[32:47]
	v_mul_f32_e32 v214, 0x3e000000, v214
	v_add3_u32 v223, s1, v78, v130
	ds_read_b128 v[182:185], v223 offset:9216
	ds_read_b128 v[186:189], v223 offset:13824
	ds_read_b128 v[190:193], v223 offset:9248
	ds_read_b128 v[194:197], v223 offset:13856
	ds_read_b128 v[198:201], v223 offset:9280
	ds_read_b128 v[202:205], v223 offset:13888
	ds_read_b128 v[206:209], v223 offset:9312
	ds_read_b128 v[210:213], v223 offset:13920
	v_mul_f32_e32 v215, s70, v214
	v_mul_f32_e32 v216, s71, v214
	v_mul_f32_e32 v217, s72, v214
	v_mul_f32_e32 v218, s73, v214
	v_mul_f32_e32 v219, s74, v214
	v_mul_f32_e32 v220, s75, v214
	v_mul_f32_e32 v221, s76, v214
	v_mul_f32_e32 v222, s77, v214
	s_nop 3
	v_mul_f32_e32 v48, v215, v48
	v_mul_f32_e32 v49, v215, v49
	v_mul_f32_e32 v50, v215, v50
	v_mul_f32_e32 v51, v215, v51
	v_mul_f32_e32 v52, v216, v52
	v_mul_f32_e32 v53, v216, v53
	v_mul_f32_e32 v54, v216, v54
	v_mul_f32_e32 v55, v216, v55
	v_mul_f32_e32 v56, v217, v56
	v_mul_f32_e32 v57, v217, v57
	v_mul_f32_e32 v58, v217, v58
	v_mul_f32_e32 v59, v217, v59
	v_mul_f32_e32 v60, v218, v60
	v_mul_f32_e32 v61, v218, v61
	v_mul_f32_e32 v62, v218, v62
	v_mul_f32_e32 v63, v218, v63
	v_mul_f32_e32 v48, s78, v48
	v_mul_f32_e32 v49, s79, v49
	v_mul_f32_e32 v50, s80, v50
	v_mul_f32_e32 v51, s81, v51
	v_mul_f32_e32 v52, s78, v52
	v_mul_f32_e32 v53, s79, v53
	v_mul_f32_e32 v54, s80, v54
	v_mul_f32_e32 v55, s81, v55
	v_mul_f32_e32 v56, s78, v56
	v_mul_f32_e32 v57, s79, v57
	v_mul_f32_e32 v58, s80, v58
	v_mul_f32_e32 v59, s81, v59
	v_mul_f32_e32 v60, s78, v60
	v_mul_f32_e32 v61, s79, v61
	v_mul_f32_e32 v62, s80, v62
	v_mul_f32_e32 v63, s81, v63
	v_cvt_pk_bf16_f32 v48, v48, v49
	v_cvt_pk_bf16_f32 v49, v50, v51
	v_cvt_pk_bf16_f32 v50, v52, v53
	v_cvt_pk_bf16_f32 v51, v54, v55
	v_cvt_pk_bf16_f32 v56, v56, v57
	v_cvt_pk_bf16_f32 v57, v58, v59
	v_cvt_pk_bf16_f32 v58, v60, v61
	v_cvt_pk_bf16_f32 v59, v62, v63
	s_waitcnt lgkmcnt(6)
	v_mfma_f32_32x32x16_bf16 v[0:15], v[182:185], v[48:51], v[0:15]
	v_mfma_f32_32x32x16_bf16 v[16:31], v[186:189], v[48:51], v[16:31]
	v_mul_f32_e32 v32, v219, v32
	v_mul_f32_e32 v33, v219, v33
	v_mul_f32_e32 v34, v219, v34
	v_mul_f32_e32 v35, v219, v35
	v_mul_f32_e32 v36, v220, v36
	v_mul_f32_e32 v37, v220, v37
	v_mul_f32_e32 v38, v220, v38
	v_mul_f32_e32 v39, v220, v39
	v_mul_f32_e32 v40, v221, v40
	v_mul_f32_e32 v41, v221, v41
	v_mul_f32_e32 v42, v221, v42
	v_mul_f32_e32 v43, v221, v43
	v_mul_f32_e32 v44, v222, v44
	v_mul_f32_e32 v45, v222, v45
	v_mul_f32_e32 v46, v222, v46
	v_mul_f32_e32 v47, v222, v47
	v_mul_f32_e32 v32, s78, v32
	v_mul_f32_e32 v33, s79, v33
	v_mul_f32_e32 v34, s80, v34
	v_mul_f32_e32 v35, s81, v35
	v_mul_f32_e32 v36, s78, v36
	v_mul_f32_e32 v37, s79, v37
	v_mul_f32_e32 v38, s80, v38
	v_mul_f32_e32 v39, s81, v39
	v_mul_f32_e32 v40, s78, v40
	v_mul_f32_e32 v41, s79, v41
	v_mul_f32_e32 v42, s80, v42
	v_mul_f32_e32 v43, s81, v43
	v_mul_f32_e32 v44, s78, v44
	v_mul_f32_e32 v45, s79, v45
	v_mul_f32_e32 v46, s80, v46
	v_mul_f32_e32 v47, s81, v47
	s_waitcnt lgkmcnt(4)
	v_mfma_f32_32x32x16_bf16 v[0:15], v[190:193], v[56:59], v[0:15]
	v_mfma_f32_32x32x16_bf16 v[16:31], v[194:197], v[56:59], v[16:31]
	v_cvt_pk_bf16_f32 v32, v32, v33
	v_cvt_pk_bf16_f32 v33, v34, v35
	v_cvt_pk_bf16_f32 v34, v36, v37
	v_cvt_pk_bf16_f32 v35, v38, v39
	v_cvt_pk_bf16_f32 v40, v40, v41
	v_cvt_pk_bf16_f32 v41, v42, v43
	v_cvt_pk_bf16_f32 v42, v44, v45
	v_cvt_pk_bf16_f32 v43, v46, v47
	s_waitcnt lgkmcnt(2)
	v_mfma_f32_32x32x16_bf16 v[0:15], v[198:201], v[32:35], v[0:15]
	v_mfma_f32_32x32x16_bf16 v[16:31], v[202:205], v[32:35], v[16:31]
	s_waitcnt lgkmcnt(0)
	v_mfma_f32_32x32x16_bf16 v[0:15], v[206:209], v[40:43], v[0:15]
	v_mfma_f32_32x32x16_bf16 v[16:31], v[210:213], v[40:43], v[16:31]
	s_sub_i32 s20, s20, 64
	s_cmpk_eq_i32 s20, 0xff40
	s_branch .Lret_tail
.Lret_lean_b:
	s_and_b32 s0, s6, 1
	s_mul_i32 s1, s0, 0x4800
	v_add_u32_e32 v223, s1, v81
	global_load_dwordx4 v[68:71], v[76:77], off
	global_load_dwordx4 v[64:67], v[74:75], off
	ds_read_b128 v[182:185], v223
	ds_read_b128 v[186:189], v223 offset:32
	ds_read_b128 v[190:193], v223 offset:64
	ds_read_b128 v[194:197], v223 offset:96
	ds_read_b128 v[198:201], v223 offset:4608
	ds_read_b128 v[202:205], v223 offset:4640
	ds_read_b128 v[206:209], v223 offset:4672
	ds_read_b128 v[210:213], v223 offset:4704
	s_xor_b32 s0, s0, 1
	s_mulk_i32 s0, 0x4800
	s_add_i32 s6, s6, 1
	v_lshl_add_u64 v[74:75], v[74:75], 0, s[30:31]
	v_lshl_add_u64 v[76:77], v[76:77], 0, s[8:9]
	v_add_u32_e32 v214, s20, v82
	v_sub_u32_e32 v214, 0, v214
	v_cvt_f32_i32_e32 v214, v214
	v_mul_f32_e32 v214, v117, v214
	v_exp_f32_e32 v214, v214
	s_waitcnt lgkmcnt(7)
	v_mfma_f32_32x32x16_bf16 v[48:63], v[182:185], v[108:111], 0
	s_waitcnt lgkmcnt(6)
	v_mfma_f32_32x32x16_bf16 v[48:63], v[186:189], v[104:107], v[48:63]
	s_waitcnt lgkmcnt(5)
	v_mfma_f32_32x32x16_bf16 v[48:63], v[190:193], v[100:103], v[48:63]
	s_waitcnt lgkmcnt(4)
	v_mfma_f32_32x32x16_bf16 v[48:63], v[194:197], v[96:99], v[48:63]
	s_waitcnt lgkmcnt(3)
	v_mfma_f32_32x32x16_bf16 v[32:47], v[198:201], v[108:111], 0
	s_waitcnt lgkmcnt(2)
	v_mfma_f32_32x32x16_bf16 v[32:47], v[202:205], v[104:107], v[32:47]
	s_waitcnt lgkmcnt(1)
	v_mfma_f32_32x32x16_bf16 v[32:47], v[206:209], v[100:103], v[32:47]
	s_waitcnt lgkmcnt(0)
	v_mfma_f32_32x32x16_bf16 v[32:47], v[210:213], v[96:99], v[32:47]
	v_mul_f32_e32 v214, 0x3e000000, v214
	v_add3_u32 v223, s1, v78, v130
	ds_read_b128 v[182:185], v223 offset:9216
	ds_read_b128 v[186:189], v223 offset:13824
	ds_read_b128 v[190:193], v223 offset:9248
	ds_read_b128 v[194:197], v223 offset:13856
	ds_read_b128 v[198:201], v223 offset:9280
	ds_read_b128 v[202:205], v223 offset:13888
	ds_read_b128 v[206:209], v223 offset:9312
	ds_read_b128 v[210:213], v223 offset:13920
	v_mul_f32_e32 v215, s82, v214
	v_mul_f32_e32 v216, s83, v214
	v_mul_f32_e32 v217, s84, v214
	v_mul_f32_e32 v218, s85, v214
	v_mul_f32_e32 v219, s86, v214
	v_mul_f32_e32 v220, s87, v214
	v_mul_f32_e32 v221, s88, v214
	v_mul_f32_e32 v222, s89, v214
	s_nop 3
	v_mul_f32_e32 v48, v215, v48
	v_mul_f32_e32 v49, v215, v49
	v_mul_f32_e32 v50, v215, v50
	v_mul_f32_e32 v51, v215, v51
	v_mul_f32_e32 v52, v216, v52
	v_mul_f32_e32 v53, v216, v53
	v_mul_f32_e32 v54, v216, v54
	v_mul_f32_e32 v55, v216, v55
	v_mul_f32_e32 v56, v217, v56
	v_mul_f32_e32 v57, v217, v57
	v_mul_f32_e32 v58, v217, v58
	v_mul_f32_e32 v59, v217, v59
	v_mul_f32_e32 v60, v218, v60
	v_mul_f32_e32 v61, v218, v61
	v_mul_f32_e32 v62, v218, v62
	v_mul_f32_e32 v63, v218, v63
	v_mul_f32_e32 v48, s90, v48
	v_mul_f32_e32 v49, s91, v49
	v_mul_f32_e32 v50, s92, v50
	v_mul_f32_e32 v51, s93, v51
	v_mul_f32_e32 v52, s90, v52
	v_mul_f32_e32 v53, s91, v53
	v_mul_f32_e32 v54, s92, v54
	v_mul_f32_e32 v55, s93, v55
	v_mul_f32_e32 v56, s90, v56
	v_mul_f32_e32 v57, s91, v57
	v_mul_f32_e32 v58, s92, v58
	v_mul_f32_e32 v59, s93, v59
	v_mul_f32_e32 v60, s90, v60
	v_mul_f32_e32 v61, s91, v61
	v_mul_f32_e32 v62, s92, v62
	v_mul_f32_e32 v63, s93, v63
	v_cvt_pk_bf16_f32 v48, v48, v49
	v_cvt_pk_bf16_f32 v49, v50, v51
	v_cvt_pk_bf16_f32 v50, v52, v53
	v_cvt_pk_bf16_f32 v51, v54, v55
	v_cvt_pk_bf16_f32 v56, v56, v57
	v_cvt_pk_bf16_f32 v57, v58, v59
	v_cvt_pk_bf16_f32 v58, v60, v61
	v_cvt_pk_bf16_f32 v59, v62, v63
	s_waitcnt lgkmcnt(6)
	v_mfma_f32_32x32x16_bf16 v[0:15], v[182:185], v[48:51], v[0:15]
	v_mfma_f32_32x32x16_bf16 v[16:31], v[186:189], v[48:51], v[16:31]
	v_mul_f32_e32 v32, v219, v32
	v_mul_f32_e32 v33, v219, v33
	v_mul_f32_e32 v34, v219, v34
	v_mul_f32_e32 v35, v219, v35
	v_mul_f32_e32 v36, v220, v36
	v_mul_f32_e32 v37, v220, v37
	v_mul_f32_e32 v38, v220, v38
	v_mul_f32_e32 v39, v220, v39
	v_mul_f32_e32 v40, v221, v40
	v_mul_f32_e32 v41, v221, v41
	v_mul_f32_e32 v42, v221, v42
	v_mul_f32_e32 v43, v221, v43
	v_mul_f32_e32 v44, v222, v44
	v_mul_f32_e32 v45, v222, v45
	v_mul_f32_e32 v46, v222, v46
	v_mul_f32_e32 v47, v222, v47
	v_mul_f32_e32 v32, s90, v32
	v_mul_f32_e32 v33, s91, v33
	v_mul_f32_e32 v34, s92, v34
	v_mul_f32_e32 v35, s93, v35
	v_mul_f32_e32 v36, s90, v36
	v_mul_f32_e32 v37, s91, v37
	v_mul_f32_e32 v38, s92, v38
	v_mul_f32_e32 v39, s93, v39
	v_mul_f32_e32 v40, s90, v40
	v_mul_f32_e32 v41, s91, v41
	v_mul_f32_e32 v42, s92, v42
	v_mul_f32_e32 v43, s93, v43
	v_mul_f32_e32 v44, s90, v44
	v_mul_f32_e32 v45, s91, v45
	v_mul_f32_e32 v46, s92, v46
	v_mul_f32_e32 v47, s93, v47
	s_waitcnt lgkmcnt(4)
	v_mfma_f32_32x32x16_bf16 v[0:15], v[190:193], v[56:59], v[0:15]
	v_mfma_f32_32x32x16_bf16 v[16:31], v[194:197], v[56:59], v[16:31]
	v_cvt_pk_bf16_f32 v32, v32, v33
	v_cvt_pk_bf16_f32 v33, v34, v35
	v_cvt_pk_bf16_f32 v34, v36, v37
	v_cvt_pk_bf16_f32 v35, v38, v39
	v_cvt_pk_bf16_f32 v40, v40, v41
	v_cvt_pk_bf16_f32 v41, v42, v43
	v_cvt_pk_bf16_f32 v42, v44, v45
	v_cvt_pk_bf16_f32 v43, v46, v47
	s_waitcnt lgkmcnt(2)
	v_mfma_f32_32x32x16_bf16 v[0:15], v[198:201], v[32:35], v[0:15]
	v_mfma_f32_32x32x16_bf16 v[16:31], v[202:205], v[32:35], v[16:31]
	s_waitcnt lgkmcnt(0)
	v_mfma_f32_32x32x16_bf16 v[0:15], v[206:209], v[40:43], v[0:15]
	v_mfma_f32_32x32x16_bf16 v[16:31], v[210:213], v[40:43], v[16:31]
	s_sub_i32 s20, s20, 64
	s_cmpk_eq_i32 s20, 0xff40
	s_branch .Lret_tail
.LBB0_1184:
	s_add_i32 s95, s94, s20
	s_cmp_ge_i32 s95, 64
	s_cbranch_scc1 .Lret_lean_f
	s_cmp_le_i32 s95, -32
	s_cbranch_scc1 .Lret_lean_b
	s_and_b32 s0, s6, 1
	s_mul_i32 s1, s0, 0x4800
	s_add_i32 s1, s1, 0
	v_add_u32_e32 v83, s1, v81
	global_load_dwordx4 v[68:71], v[76:77], off
	global_load_dwordx4 v[64:67], v[74:75], off
	ds_read_b128 v[32:35], v83 offset:4608
	ds_read_b128 v[36:39], v83
	ds_read_b128 v[84:87], v83 offset:32
	ds_read_b128 v[88:91], v83 offset:4640
	s_xor_b32 s0, s0, 1
	s_waitcnt lgkmcnt(2)
	v_mfma_f32_32x32x16_bf16 v[48:63], v[36:39], v[108:111], 0
	s_mulk_i32 s0, 0x4800
	s_add_i32 s0, s0, 0
	s_add_i32 s6, s6, 1
	v_lshl_add_u64 v[74:75], v[74:75], 0, s[30:31]
	v_lshl_add_u64 v[76:77], v[76:77], 0, s[8:9]
	v_mfma_f32_32x32x16_bf16 v[32:47], v[32:35], v[108:111], 0
	s_waitcnt lgkmcnt(1)
	v_mfma_f32_32x32x16_bf16 v[48:63], v[84:87], v[104:107], v[48:63]
	s_waitcnt lgkmcnt(0)
	v_mfma_f32_32x32x16_bf16 v[32:47], v[88:91], v[104:107], v[32:47]
	ds_read_b128 v[84:87], v83 offset:64
	ds_read_b128 v[88:91], v83 offset:4672
	s_waitcnt lgkmcnt(1)
	v_mfma_f32_32x32x16_bf16 v[48:63], v[84:87], v[100:103], v[48:63]
	s_waitcnt lgkmcnt(0)
	v_mfma_f32_32x32x16_bf16 v[32:47], v[88:91], v[100:103], v[32:47]
	ds_read_b128 v[84:87], v83 offset:96
	ds_read_b128 v[88:91], v83 offset:4704
	v_add_u32_e32 v83, s20, v82
	v_cmp_gt_i32_e32 vcc, 0, v83
	s_sub_i32 s20, s20, 64
	s_cmpk_eq_i32 s20, 0xff40
	s_waitcnt lgkmcnt(1)
	v_mfma_f32_32x32x16_bf16 v[48:63], v[84:87], v[96:99], v[48:63]
	v_sub_u32_e32 v84, 0, v83
	v_max_i32_e32 v84, v83, v84
	v_cvt_f32_u32_e32 v84, v84
	v_cndmask_b32_e32 v86, v115, v117, vcc
	v_subrev_u32_e32 v85, 32, v83
	v_cmp_gt_i32_e32 vcc, 0, v85
	v_mul_f32_e32 v84, v86, v84
	v_sub_u32_e32 v86, 32, v83
	v_max_i32_e32 v86, v85, v86
	v_cvt_f32_u32_e32 v86, v86
	v_cndmask_b32_e32 v85, v115, v117, vcc
	s_waitcnt lgkmcnt(0)
	v_mfma_f32_32x32x16_bf16 v[32:47], v[88:91], v[96:99], v[32:47]
	v_sub_u32_e32 v88, 1, v83
	v_mul_f32_e32 v85, v85, v86
	v_exp_f32_e32 v86, v85
	v_add_u32_e32 v85, -1, v83
	v_max_i32_e32 v88, v85, v88
	v_cvt_f32_u32_e32 v88, v88
	v_cmp_gt_i32_e32 vcc, 0, v85
	v_subrev_u32_e32 v87, 33, v83
	v_exp_f32_e32 v84, v84
	v_cndmask_b32_e32 v85, v115, v117, vcc
	v_mul_f32_e32 v85, v85, v88
	v_sub_u32_e32 v88, 33, v83
	v_max_i32_e32 v88, v87, v88
	v_cvt_f32_u32_e32 v88, v88
	v_cmp_gt_i32_e32 vcc, 0, v87
	v_exp_f32_e32 v85, v85
	s_nop 0
	v_cndmask_b32_e32 v87, v115, v117, vcc
	v_mul_f32_e32 v87, v87, v88
	v_exp_f32_e32 v87, v87
	v_pk_mul_f32 v[84:85], v[84:85], s[2:3] op_sel_hi:[1,0]
	v_sub_u32_e32 v88, 3, v83
	v_pk_mul_f32 v[48:49], v[84:85], v[48:49]
	v_pk_mul_f32 v[84:85], v[86:87], s[2:3] op_sel_hi:[1,0]
	v_sub_u32_e32 v86, 2, v83
	v_pk_mul_f32 v[32:33], v[84:85], v[32:33]
	v_add_u32_e32 v84, -2, v83
	v_max_i32_e32 v86, v84, v86
	v_cvt_f32_u32_e32 v86, v86
	v_cmp_gt_i32_e32 vcc, 0, v84
	v_subrev_u32_e32 v85, 34, v83
	v_subrev_u32_e32 v87, 35, v83
	v_cndmask_b32_e32 v84, v115, v117, vcc
	v_mul_f32_e32 v84, v84, v86
	v_sub_u32_e32 v86, 34, v83
	v_max_i32_e32 v86, v85, v86
	v_cvt_f32_u32_e32 v86, v86
	v_cmp_gt_i32_e32 vcc, 0, v85
	v_exp_f32_e32 v84, v84
	v_cvt_pk_bf16_f32 v32, v32, v33
	v_cndmask_b32_e32 v85, v115, v117, vcc
	v_mul_f32_e32 v85, v85, v86
	v_exp_f32_e32 v86, v85
	v_add_u32_e32 v85, -3, v83
	v_max_i32_e32 v88, v85, v88
	v_cvt_f32_u32_e32 v88, v88
	v_cmp_gt_i32_e32 vcc, 0, v85
	s_nop 1
	v_cndmask_b32_e32 v85, v115, v117, vcc
	v_mul_f32_e32 v85, v85, v88
	v_sub_u32_e32 v88, 35, v83
	v_max_i32_e32 v88, v87, v88
	v_cvt_f32_u32_e32 v88, v88
	v_cmp_gt_i32_e32 vcc, 0, v87
	v_exp_f32_e32 v85, v85
	s_nop 0
	v_cndmask_b32_e32 v87, v115, v117, vcc
	v_mul_f32_e32 v87, v87, v88
	v_exp_f32_e32 v87, v87
	v_pk_mul_f32 v[84:85], v[84:85], s[2:3] op_sel_hi:[1,0]
	v_sub_u32_e32 v88, 9, v83
	v_pk_mul_f32 v[50:51], v[84:85], v[50:51]
	v_pk_mul_f32 v[84:85], v[86:87], s[2:3] op_sel_hi:[1,0]
	v_sub_u32_e32 v86, 8, v83
	v_pk_mul_f32 v[84:85], v[84:85], v[34:35]
	v_add_u32_e32 v34, -8, v83
	v_max_i32_e32 v86, v34, v86
	v_cvt_f32_u32_e32 v86, v86
	v_cmp_gt_i32_e32 vcc, 0, v34
	v_subrev_u32_e32 v35, 40, v83
	v_subrev_u32_e32 v87, 41, v83
	v_cndmask_b32_e32 v34, v115, v117, vcc
	v_mul_f32_e32 v34, v34, v86
	v_sub_u32_e32 v86, 40, v83
	v_max_i32_e32 v86, v35, v86
	v_cvt_f32_u32_e32 v86, v86
	v_cmp_gt_i32_e32 vcc, 0, v35
	v_exp_f32_e32 v34, v34
	v_cvt_pk_bf16_f32 v33, v84, v85
	v_cndmask_b32_e32 v35, v115, v117, vcc
	v_mul_f32_e32 v35, v35, v86
	v_exp_f32_e32 v86, v35
	v_add_u32_e32 v35, -9, v83
	v_max_i32_e32 v88, v35, v88
	v_cvt_f32_u32_e32 v88, v88
	v_cmp_gt_i32_e32 vcc, 0, v35
	s_nop 1
	v_cndmask_b32_e32 v35, v115, v117, vcc
	v_mul_f32_e32 v35, v35, v88
	v_sub_u32_e32 v88, 41, v83
	v_max_i32_e32 v88, v87, v88
	v_cvt_f32_u32_e32 v88, v88
	v_cmp_gt_i32_e32 vcc, 0, v87
	v_exp_f32_e32 v35, v35
	s_nop 0
	v_cndmask_b32_e32 v87, v115, v117, vcc
	v_mul_f32_e32 v87, v87, v88
	v_exp_f32_e32 v87, v87
	v_pk_mul_f32 v[34:35], v[34:35], s[2:3] op_sel_hi:[1,0]
	v_sub_u32_e32 v88, 11, v83
	v_pk_mul_f32 v[52:53], v[34:35], v[52:53]
	v_pk_mul_f32 v[34:35], v[86:87], s[2:3] op_sel_hi:[1,0]
	s_nop 0
	v_pk_mul_f32 v[86:87], v[34:35], v[36:37]
	v_add_u32_e32 v34, -10, v83
	v_sub_u32_e32 v36, 10, v83
	v_max_i32_e32 v36, v34, v36
	v_cvt_f32_u32_e32 v36, v36
	v_cmp_gt_i32_e32 vcc, 0, v34
	v_subrev_u32_e32 v35, 42, v83
	v_subrev_u32_e32 v37, 43, v83
	v_cndmask_b32_e32 v34, v115, v117, vcc
	v_mul_f32_e32 v34, v34, v36
	v_sub_u32_e32 v36, 42, v83
	v_max_i32_e32 v36, v35, v36
	v_cvt_f32_u32_e32 v36, v36
	v_cmp_gt_i32_e32 vcc, 0, v35
	v_exp_f32_e32 v34, v34
	s_nop 0
	v_cndmask_b32_e32 v35, v115, v117, vcc
	v_mul_f32_e32 v35, v35, v36
	v_exp_f32_e32 v36, v35
	v_add_u32_e32 v35, -11, v83
	v_max_i32_e32 v88, v35, v88
	v_cvt_f32_u32_e32 v88, v88
	v_cmp_gt_i32_e32 vcc, 0, v35
	s_nop 1
	v_cndmask_b32_e32 v35, v115, v117, vcc
	v_mul_f32_e32 v35, v35, v88
	v_sub_u32_e32 v88, 43, v83
	v_max_i32_e32 v88, v37, v88
	v_cvt_f32_u32_e32 v88, v88
	v_cmp_gt_i32_e32 vcc, 0, v37
	v_exp_f32_e32 v35, v35
	s_nop 0
	v_cndmask_b32_e32 v37, v115, v117, vcc
	v_mul_f32_e32 v37, v37, v88
	v_exp_f32_e32 v37, v37
	v_pk_mul_f32 v[34:35], v[34:35], s[2:3] op_sel_hi:[1,0]
	s_nop 0
	v_pk_mul_f32 v[54:55], v[34:35], v[54:55]
	v_pk_mul_f32 v[34:35], v[36:37], s[2:3] op_sel_hi:[1,0]
	v_sub_u32_e32 v36, 16, v83
	v_pk_mul_f32 v[88:89], v[34:35], v[38:39]
	v_add_u32_e32 v34, -16, v83
	v_max_i32_e32 v36, v34, v36
	v_cvt_f32_u32_e32 v36, v36
	v_cmp_gt_i32_e32 vcc, 0, v34
	v_subrev_u32_e32 v35, 48, v83
	v_sub_u32_e32 v38, 17, v83
	v_cndmask_b32_e32 v34, v115, v117, vcc
	v_mul_f32_e32 v34, v34, v36
	v_sub_u32_e32 v36, 48, v83
	v_max_i32_e32 v36, v35, v36
	v_cvt_f32_u32_e32 v36, v36
	v_cmp_gt_i32_e32 vcc, 0, v35
	v_subrev_u32_e32 v37, 49, v83
	v_exp_f32_e32 v34, v34
	v_cndmask_b32_e32 v35, v115, v117, vcc
	v_mul_f32_e32 v35, v35, v36
	v_exp_f32_e32 v36, v35
	v_subrev_u32_e32 v35, 17, v83
	v_max_i32_e32 v38, v35, v38
	v_cvt_f32_u32_e32 v38, v38
	v_cmp_gt_i32_e32 vcc, 0, v35
	s_nop 1
	v_cndmask_b32_e32 v35, v115, v117, vcc
	v_mul_f32_e32 v35, v35, v38
	v_sub_u32_e32 v38, 49, v83
	v_max_i32_e32 v38, v37, v38
	v_cvt_f32_u32_e32 v38, v38
	v_cmp_gt_i32_e32 vcc, 0, v37
	v_exp_f32_e32 v35, v35
	s_nop 0
	v_cndmask_b32_e32 v37, v115, v117, vcc
	v_mul_f32_e32 v37, v37, v38
	v_exp_f32_e32 v37, v37
	v_pk_mul_f32 v[34:35], v[34:35], s[2:3] op_sel_hi:[1,0]
	v_sub_u32_e32 v38, 19, v83
	v_pk_mul_f32 v[56:57], v[34:35], v[56:57]
	v_pk_mul_f32 v[34:35], v[36:37], s[2:3] op_sel_hi:[1,0]
	v_sub_u32_e32 v36, 18, v83
	v_pk_mul_f32 v[90:91], v[34:35], v[40:41]
	v_subrev_u32_e32 v34, 18, v83
	v_max_i32_e32 v36, v34, v36
	v_cvt_f32_u32_e32 v36, v36
	v_cmp_gt_i32_e32 vcc, 0, v34
	v_subrev_u32_e32 v35, 50, v83
	v_subrev_u32_e32 v37, 51, v83
	v_cndmask_b32_e32 v34, v115, v117, vcc
	v_mul_f32_e32 v34, v34, v36
	v_sub_u32_e32 v36, 50, v83
	v_max_i32_e32 v36, v35, v36
	v_cvt_f32_u32_e32 v36, v36
	v_cmp_gt_i32_e32 vcc, 0, v35
	v_exp_f32_e32 v34, v34
	s_nop 0
	v_cndmask_b32_e32 v35, v115, v117, vcc
	v_mul_f32_e32 v35, v35, v36
	v_exp_f32_e32 v36, v35
	v_subrev_u32_e32 v35, 19, v83
	v_max_i32_e32 v38, v35, v38
	v_cvt_f32_u32_e32 v38, v38
	v_cmp_gt_i32_e32 vcc, 0, v35
	s_nop 1
	v_cndmask_b32_e32 v35, v115, v117, vcc
	v_mul_f32_e32 v35, v35, v38
	v_sub_u32_e32 v38, 51, v83
	v_max_i32_e32 v38, v37, v38
	v_cvt_f32_u32_e32 v38, v38
	v_cmp_gt_i32_e32 vcc, 0, v37
	v_exp_f32_e32 v35, v35
	s_nop 0
	v_cndmask_b32_e32 v37, v115, v117, vcc
	v_mul_f32_e32 v37, v37, v38
	v_exp_f32_e32 v37, v37
	v_pk_mul_f32 v[34:35], v[34:35], s[2:3] op_sel_hi:[1,0]
	v_sub_u32_e32 v38, 25, v83
	v_pk_mul_f32 v[58:59], v[34:35], v[58:59]
	v_pk_mul_f32 v[34:35], v[36:37], s[2:3] op_sel_hi:[1,0]
	v_sub_u32_e32 v36, 24, v83
	v_pk_mul_f32 v[92:93], v[34:35], v[42:43]
	v_subrev_u32_e32 v34, 24, v83
	v_max_i32_e32 v36, v34, v36
	v_cvt_f32_u32_e32 v36, v36
	v_cmp_gt_i32_e32 vcc, 0, v34
	v_subrev_u32_e32 v35, 56, v83
	v_subrev_u32_e32 v37, 57, v83
	v_cndmask_b32_e32 v34, v115, v117, vcc
	v_mul_f32_e32 v34, v34, v36
	v_sub_u32_e32 v36, 56, v83
	v_max_i32_e32 v36, v35, v36
	v_cvt_f32_u32_e32 v36, v36
	v_cmp_gt_i32_e32 vcc, 0, v35
	v_exp_f32_e32 v34, v34
	s_nop 0
	v_cndmask_b32_e32 v35, v115, v117, vcc
	v_mul_f32_e32 v35, v35, v36
	v_exp_f32_e32 v36, v35
	v_subrev_u32_e32 v35, 25, v83
	v_max_i32_e32 v38, v35, v38
	v_cvt_f32_u32_e32 v38, v38
	v_cmp_gt_i32_e32 vcc, 0, v35
	s_nop 1
	v_cndmask_b32_e32 v35, v115, v117, vcc
	v_mul_f32_e32 v35, v35, v38
	v_sub_u32_e32 v38, 57, v83
	v_max_i32_e32 v38, v37, v38
	v_cvt_f32_u32_e32 v38, v38
	v_cmp_gt_i32_e32 vcc, 0, v37
	v_exp_f32_e32 v35, v35
	s_nop 0
	v_cndmask_b32_e32 v37, v115, v117, vcc
	v_mul_f32_e32 v37, v37, v38
	v_exp_f32_e32 v37, v37
	v_pk_mul_f32 v[34:35], v[34:35], s[2:3] op_sel_hi:[1,0]
	v_sub_u32_e32 v38, 27, v83
	v_pk_mul_f32 v[60:61], v[34:35], v[60:61]
	v_pk_mul_f32 v[34:35], v[36:37], s[2:3] op_sel_hi:[1,0]
	v_sub_u32_e32 v36, 26, v83
	v_pk_mul_f32 v[94:95], v[34:35], v[44:45]
	v_subrev_u32_e32 v34, 26, v83
	v_max_i32_e32 v36, v34, v36
	v_cvt_f32_u32_e32 v36, v36
	v_cmp_gt_i32_e32 vcc, 0, v34
	v_subrev_u32_e32 v35, 58, v83
	v_subrev_u32_e32 v37, 59, v83
	v_cndmask_b32_e32 v34, v115, v117, vcc
	v_mul_f32_e32 v34, v34, v36
	v_sub_u32_e32 v36, 58, v83
	v_max_i32_e32 v36, v35, v36
	v_cvt_f32_u32_e32 v36, v36
	v_cmp_gt_i32_e32 vcc, 0, v35
	v_exp_f32_e32 v34, v34
	s_nop 0
	v_cndmask_b32_e32 v35, v115, v117, vcc
	v_mul_f32_e32 v35, v35, v36
	v_exp_f32_e32 v36, v35
	v_subrev_u32_e32 v35, 27, v83
	v_max_i32_e32 v38, v35, v38
	v_cvt_f32_u32_e32 v38, v38
	v_cmp_gt_i32_e32 vcc, 0, v35
	s_nop 1
	v_cndmask_b32_e32 v35, v115, v117, vcc
	v_mul_f32_e32 v35, v35, v38
	v_sub_u32_e32 v38, 59, v83
	v_max_i32_e32 v38, v37, v38
	v_cvt_f32_u32_e32 v38, v38
	v_cmp_gt_i32_e32 vcc, 0, v37
	v_exp_f32_e32 v35, v35
	s_nop 0
	v_cndmask_b32_e32 v37, v115, v117, vcc
	v_mul_f32_e32 v37, v37, v38
	v_exp_f32_e32 v37, v37
	v_pk_mul_f32 v[34:35], v[34:35], s[2:3] op_sel_hi:[1,0]
	s_nop 0
	v_pk_mul_f32 v[62:63], v[34:35], v[62:63]
	v_pk_mul_f32 v[34:35], v[36:37], s[2:3] op_sel_hi:[1,0]
	v_cvt_pk_bf16_f32 v36, v52, v53
	v_pk_mul_f32 v[118:119], v[34:35], v[46:47]
	v_cvt_pk_bf16_f32 v35, v50, v51
	v_add3_u32 v50, s1, v78, v130
	v_cvt_pk_bf16_f32 v34, v48, v49
	ds_read_b128 v[38:41], v50 offset:13824
	ds_read_b128 v[42:45], v50 offset:9216
	ds_read_b128 v[46:49], v50 offset:9248
	v_cvt_pk_bf16_f32 v37, v54, v55
	s_waitcnt lgkmcnt(2)
	s_nop 0
	v_mfma_f32_32x32x16_bf16 v[16:31], v[38:41], v[34:37], v[16:31]
	ds_read_b128 v[38:41], v50 offset:13856
	s_waitcnt lgkmcnt(2)
	v_mfma_f32_32x32x16_bf16 v[0:15], v[42:45], v[34:37], v[0:15]
	v_cvt_pk_bf16_f32 v34, v56, v57
	v_cvt_pk_bf16_f32 v35, v58, v59
	v_cvt_pk_bf16_f32 v36, v60, v61
	v_cvt_pk_bf16_f32 v37, v62, v63
	s_waitcnt lgkmcnt(1)
	s_nop 0
	v_mfma_f32_32x32x16_bf16 v[0:15], v[46:49], v[34:37], v[0:15]
	s_waitcnt lgkmcnt(0)
	v_mfma_f32_32x32x16_bf16 v[16:31], v[38:41], v[34:37], v[16:31]
	ds_read_b128 v[36:39], v50 offset:9280
	ds_read_b128 v[40:43], v50 offset:13888
	v_cvt_pk_bf16_f32 v34, v86, v87
	v_cvt_pk_bf16_f32 v35, v88, v89
	s_waitcnt lgkmcnt(1)
	s_nop 0
	v_mfma_f32_32x32x16_bf16 v[0:15], v[36:39], v[32:35], v[0:15]
	s_waitcnt lgkmcnt(0)
	v_mfma_f32_32x32x16_bf16 v[16:31], v[40:43], v[32:35], v[16:31]
	ds_read_b128 v[36:39], v50 offset:9312
	ds_read_b128 v[40:43], v50 offset:13920
	v_cvt_pk_bf16_f32 v32, v90, v91
	v_cvt_pk_bf16_f32 v33, v92, v93
	v_cvt_pk_bf16_f32 v34, v94, v95
	v_cvt_pk_bf16_f32 v35, v118, v119
	s_waitcnt lgkmcnt(1)
	s_nop 0
	v_mfma_f32_32x32x16_bf16 v[0:15], v[36:39], v[32:35], v[0:15]
	s_waitcnt lgkmcnt(0)
	v_mfma_f32_32x32x16_bf16 v[16:31], v[40:43], v[32:35], v[16:31]
.Lret_tail:
	v_add_u32_e32 v32, s0, v79
	v_add_u32_e32 v33, s0, v80
	s_waitcnt vmcnt(1)
	ds_write_b128 v32, v[68:71]
	v_add_u32_e32 v32, 0x2000, v33
	s_waitcnt vmcnt(0)
	ds_write2_b64 v32, v[64:65], v[66:67] offset0:128 offset1:130
	s_waitcnt lgkmcnt(0)
	s_barrier
	s_cbranch_scc0 .LBB0_1184
	v_add_u32_e32 v74, 0, v81
	ds_read_b128 v[32:35], v74 offset:23040
	ds_read_b128 v[36:39], v74 offset:18432
	ds_read_b128 v[64:67], v74 offset:18464
	ds_read_b128 v[68:71], v74 offset:23072
	s_movk_i32 s0, 0xff3f
	s_cmp_eq_u64 s[4:5], 0
	s_waitcnt lgkmcnt(2)
	v_mfma_f32_32x32x16_bf16 v[48:63], v[36:39], v[108:111], 0
	v_mfma_f32_32x32x16_bf16 v[32:47], v[32:35], v[108:111], 0
	s_waitcnt lgkmcnt(1)
	v_mfma_f32_32x32x16_bf16 v[48:63], v[64:67], v[104:107], v[48:63]
	s_waitcnt lgkmcnt(0)
	v_mfma_f32_32x32x16_bf16 v[32:47], v[68:71], v[104:107], v[32:47]
	ds_read_b128 v[64:67], v74 offset:18496
	ds_read_b128 v[68:71], v74 offset:23104
	s_waitcnt lgkmcnt(1)
	v_mfma_f32_32x32x16_bf16 v[48:63], v[64:67], v[100:103], v[48:63]
	s_waitcnt lgkmcnt(0)
	v_mfma_f32_32x32x16_bf16 v[32:47], v[68:71], v[100:103], v[32:47]
	ds_read_b128 v[64:67], v74 offset:18528
	ds_read_b128 v[68:71], v74 offset:23136
	v_add3_u32 v74, 0, v78, v130
	s_waitcnt lgkmcnt(1)
	v_mfma_f32_32x32x16_bf16 v[48:63], v[64:67], v[96:99], v[48:63]
	v_or_b32_e32 v64, 0xc0, v114
	v_sub_u32_e32 v64, v116, v64
	v_sub_u32_e32 v66, 0, v64
	v_max_i32_e32 v66, v64, v66
	v_cvt_f32_u32_e32 v66, v66
	v_or_b32_e32 v65, 0xe0, v114
	v_cmp_gt_i32_e32 vcc, 0, v64
	v_sub_u32_e32 v65, v116, v65
	v_xad_u32 v67, v114, s0, v116
	v_cndmask_b32_e32 v64, v115, v117, vcc
	v_mul_f32_e32 v64, v64, v66
	v_sub_u32_e32 v66, 0, v65
	v_max_i32_e32 v66, v65, v66
	v_cvt_f32_u32_e32 v66, v66
	v_cmp_gt_i32_e32 vcc, 0, v65
	s_waitcnt lgkmcnt(0)
	v_mfma_f32_32x32x16_bf16 v[32:47], v[68:71], v[96:99], v[32:47]
	v_exp_f32_e32 v64, v64
	v_cndmask_b32_e32 v65, v115, v117, vcc
	v_mul_f32_e32 v65, v65, v66
	v_exp_f32_e32 v66, v65
	v_or_b32_e32 v65, 0xe1, v114
	v_sub_u32_e32 v68, v116, v65
	v_sub_u32_e32 v65, 0, v67
	v_max_i32_e32 v65, v67, v65
	v_cvt_f32_u32_e32 v65, v65
	v_cmp_gt_i32_e32 vcc, 0, v67
	s_nop 1
	v_cndmask_b32_e32 v67, v115, v117, vcc
	v_mul_f32_e32 v65, v67, v65
	v_sub_u32_e32 v67, 0, v68
	v_max_i32_e32 v67, v68, v67
	v_cvt_f32_u32_e32 v67, v67
	v_cmp_gt_i32_e32 vcc, 0, v68
	v_exp_f32_e32 v65, v65
	s_nop 0
	v_cndmask_b32_e32 v68, v115, v117, vcc
	v_mul_f32_e32 v67, v68, v67
	v_exp_f32_e32 v67, v67
	v_pk_mul_f32 v[64:65], v[64:65], s[2:3] op_sel_hi:[1,0]
	s_nop 0
	v_pk_mul_f32 v[48:49], v[64:65], v[48:49]
	v_pk_mul_f32 v[64:65], v[66:67], s[2:3] op_sel_hi:[1,0]
	v_or_b32_e32 v67, 0xe3, v114
	v_pk_mul_f32 v[32:33], v[64:65], v[32:33]
	v_or_b32_e32 v64, 0xc2, v114
	v_sub_u32_e32 v64, v116, v64
	v_sub_u32_e32 v66, 0, v64
	v_max_i32_e32 v66, v64, v66
	v_cvt_f32_u32_e32 v66, v66
	v_or_b32_e32 v65, 0xe2, v114
	v_cmp_gt_i32_e32 vcc, 0, v64
	v_sub_u32_e32 v65, v116, v65
	v_sub_u32_e32 v67, v116, v67
	v_cndmask_b32_e32 v64, v115, v117, vcc
	v_mul_f32_e32 v64, v64, v66
	v_sub_u32_e32 v66, 0, v65
	v_max_i32_e32 v66, v65, v66
	v_cvt_f32_u32_e32 v66, v66
	v_cmp_gt_i32_e32 vcc, 0, v65
	v_exp_f32_e32 v64, v64
	v_cvt_pk_bf16_f32 v48, v48, v49
	v_cndmask_b32_e32 v65, v115, v117, vcc
	v_mul_f32_e32 v65, v65, v66
	v_exp_f32_e32 v66, v65
	v_or_b32_e32 v65, 0xc3, v114
	v_sub_u32_e32 v65, v116, v65
	v_sub_u32_e32 v68, 0, v65
	v_max_i32_e32 v68, v65, v68
	v_cvt_f32_u32_e32 v68, v68
	v_cmp_gt_i32_e32 vcc, 0, v65
	v_cvt_pk_bf16_f32 v32, v32, v33
	s_nop 0
	v_cndmask_b32_e32 v65, v115, v117, vcc
	v_mul_f32_e32 v65, v65, v68
	v_sub_u32_e32 v68, 0, v67
	v_max_i32_e32 v68, v67, v68
	v_cvt_f32_u32_e32 v68, v68
	v_cmp_gt_i32_e32 vcc, 0, v67
	v_exp_f32_e32 v65, v65
	s_nop 0
	v_cndmask_b32_e32 v67, v115, v117, vcc
	v_mul_f32_e32 v67, v67, v68
	v_exp_f32_e32 v67, v67
	v_pk_mul_f32 v[64:65], v[64:65], s[2:3] op_sel_hi:[1,0]
	s_nop 0
	v_pk_mul_f32 v[50:51], v[64:65], v[50:51]
	v_pk_mul_f32 v[64:65], v[66:67], s[2:3] op_sel_hi:[1,0]
	v_or_b32_e32 v67, 0xe9, v114
	v_pk_mul_f32 v[34:35], v[64:65], v[34:35]
	v_or_b32_e32 v64, 0xc8, v114
	v_sub_u32_e32 v64, v116, v64
	v_sub_u32_e32 v66, 0, v64
	v_max_i32_e32 v66, v64, v66
	v_cvt_f32_u32_e32 v66, v66
	v_or_b32_e32 v65, 0xe8, v114
	v_cmp_gt_i32_e32 vcc, 0, v64
	v_sub_u32_e32 v65, v116, v65
	v_sub_u32_e32 v67, v116, v67
	v_cndmask_b32_e32 v64, v115, v117, vcc
	v_mul_f32_e32 v64, v64, v66
	v_sub_u32_e32 v66, 0, v65
	v_max_i32_e32 v66, v65, v66
	v_cvt_f32_u32_e32 v66, v66
	v_cmp_gt_i32_e32 vcc, 0, v65
	v_exp_f32_e32 v64, v64
	v_cvt_pk_bf16_f32 v49, v50, v51
	v_cndmask_b32_e32 v65, v115, v117, vcc
	v_mul_f32_e32 v65, v65, v66
	v_exp_f32_e32 v66, v65
	v_or_b32_e32 v65, 0xc9, v114
	v_sub_u32_e32 v65, v116, v65
	v_sub_u32_e32 v68, 0, v65
	v_max_i32_e32 v68, v65, v68
	v_cvt_f32_u32_e32 v68, v68
	v_cmp_gt_i32_e32 vcc, 0, v65
	v_cvt_pk_bf16_f32 v33, v34, v35
	s_nop 0
	v_cndmask_b32_e32 v65, v115, v117, vcc
	v_mul_f32_e32 v65, v65, v68
	v_sub_u32_e32 v68, 0, v67
	v_max_i32_e32 v68, v67, v68
	v_cvt_f32_u32_e32 v68, v68
	v_cmp_gt_i32_e32 vcc, 0, v67
	v_exp_f32_e32 v65, v65
	s_nop 0
	v_cndmask_b32_e32 v67, v115, v117, vcc
	v_mul_f32_e32 v67, v67, v68
	v_exp_f32_e32 v67, v67
	v_pk_mul_f32 v[64:65], v[64:65], s[2:3] op_sel_hi:[1,0]
	s_nop 0
	v_pk_mul_f32 v[52:53], v[64:65], v[52:53]
	v_pk_mul_f32 v[64:65], v[66:67], s[2:3] op_sel_hi:[1,0]
	v_or_b32_e32 v67, 0xeb, v114
	v_pk_mul_f32 v[36:37], v[64:65], v[36:37]
	v_or_b32_e32 v64, 0xca, v114
	v_sub_u32_e32 v64, v116, v64
	v_sub_u32_e32 v66, 0, v64
	v_max_i32_e32 v66, v64, v66
	v_cvt_f32_u32_e32 v66, v66
	v_or_b32_e32 v65, 0xea, v114
	v_cmp_gt_i32_e32 vcc, 0, v64
	v_sub_u32_e32 v65, v116, v65
	v_sub_u32_e32 v67, v116, v67
	v_cndmask_b32_e32 v64, v115, v117, vcc
	v_mul_f32_e32 v64, v64, v66
	v_sub_u32_e32 v66, 0, v65
	v_max_i32_e32 v66, v65, v66
	v_cvt_f32_u32_e32 v66, v66
	v_cmp_gt_i32_e32 vcc, 0, v65
	v_exp_f32_e32 v64, v64
	v_cvt_pk_bf16_f32 v50, v52, v53
	v_cndmask_b32_e32 v65, v115, v117, vcc
	v_mul_f32_e32 v65, v65, v66
	v_exp_f32_e32 v66, v65
	v_or_b32_e32 v65, 0xcb, v114
	v_sub_u32_e32 v65, v116, v65
	v_sub_u32_e32 v68, 0, v65
	v_max_i32_e32 v68, v65, v68
	v_cvt_f32_u32_e32 v68, v68
	v_cmp_gt_i32_e32 vcc, 0, v65
	v_cvt_pk_bf16_f32 v34, v36, v37
	s_nop 0
	v_cndmask_b32_e32 v65, v115, v117, vcc
	v_mul_f32_e32 v65, v65, v68
	v_sub_u32_e32 v68, 0, v67
	v_max_i32_e32 v68, v67, v68
	v_cvt_f32_u32_e32 v68, v68
	v_cmp_gt_i32_e32 vcc, 0, v67
	v_exp_f32_e32 v65, v65
	s_nop 0
	v_cndmask_b32_e32 v67, v115, v117, vcc
	v_mul_f32_e32 v67, v67, v68
	v_exp_f32_e32 v67, v67
	v_pk_mul_f32 v[64:65], v[64:65], s[2:3] op_sel_hi:[1,0]
	s_nop 0
	v_pk_mul_f32 v[54:55], v[64:65], v[54:55]
	v_pk_mul_f32 v[64:65], v[66:67], s[2:3] op_sel_hi:[1,0]
	v_or_b32_e32 v67, 0xf1, v114
	v_pk_mul_f32 v[38:39], v[64:65], v[38:39]
	v_or_b32_e32 v64, 0xd0, v114
	v_sub_u32_e32 v64, v116, v64
	v_sub_u32_e32 v66, 0, v64
	v_max_i32_e32 v66, v64, v66
	v_cvt_f32_u32_e32 v66, v66
	v_or_b32_e32 v65, 0xf0, v114
	v_cmp_gt_i32_e32 vcc, 0, v64
	v_sub_u32_e32 v65, v116, v65
	v_sub_u32_e32 v67, v116, v67
	v_cndmask_b32_e32 v64, v115, v117, vcc
	v_mul_f32_e32 v64, v64, v66
	v_sub_u32_e32 v66, 0, v65
	v_max_i32_e32 v66, v65, v66
	v_cvt_f32_u32_e32 v66, v66
	v_cmp_gt_i32_e32 vcc, 0, v65
	v_exp_f32_e32 v64, v64
	v_cvt_pk_bf16_f32 v51, v54, v55
	v_cndmask_b32_e32 v65, v115, v117, vcc
	v_mul_f32_e32 v65, v65, v66
	v_exp_f32_e32 v66, v65
	v_or_b32_e32 v65, 0xd1, v114
	v_sub_u32_e32 v65, v116, v65
	v_sub_u32_e32 v68, 0, v65
	v_max_i32_e32 v68, v65, v68
	v_cvt_f32_u32_e32 v68, v68
	v_cmp_gt_i32_e32 vcc, 0, v65
	v_cvt_pk_bf16_f32 v35, v38, v39
	s_nop 0
	v_cndmask_b32_e32 v65, v115, v117, vcc
	v_mul_f32_e32 v65, v65, v68
	v_sub_u32_e32 v68, 0, v67
	v_max_i32_e32 v68, v67, v68
	v_cvt_f32_u32_e32 v68, v68
	v_cmp_gt_i32_e32 vcc, 0, v67
	v_exp_f32_e32 v65, v65
	s_nop 0
	v_cndmask_b32_e32 v67, v115, v117, vcc
	v_mul_f32_e32 v67, v67, v68
	v_exp_f32_e32 v67, v67
	v_pk_mul_f32 v[64:65], v[64:65], s[2:3] op_sel_hi:[1,0]
	s_nop 0
	v_pk_mul_f32 v[56:57], v[64:65], v[56:57]
	v_pk_mul_f32 v[64:65], v[66:67], s[2:3] op_sel_hi:[1,0]
	v_or_b32_e32 v67, 0xf3, v114
	v_pk_mul_f32 v[40:41], v[64:65], v[40:41]
	v_or_b32_e32 v64, 0xd2, v114
	v_sub_u32_e32 v64, v116, v64
	v_sub_u32_e32 v66, 0, v64
	v_max_i32_e32 v66, v64, v66
	v_cvt_f32_u32_e32 v66, v66
	v_or_b32_e32 v65, 0xf2, v114
	v_cmp_gt_i32_e32 vcc, 0, v64
	v_sub_u32_e32 v65, v116, v65
	v_sub_u32_e32 v67, v116, v67
	v_cndmask_b32_e32 v64, v115, v117, vcc
	v_mul_f32_e32 v64, v64, v66
	v_sub_u32_e32 v66, 0, v65
	v_max_i32_e32 v66, v65, v66
	v_cvt_f32_u32_e32 v66, v66
	v_cmp_gt_i32_e32 vcc, 0, v65
	v_exp_f32_e32 v64, v64
	s_nop 0
	v_cndmask_b32_e32 v65, v115, v117, vcc
	v_mul_f32_e32 v65, v65, v66
	v_exp_f32_e32 v66, v65
	v_or_b32_e32 v65, 0xd3, v114
	v_sub_u32_e32 v65, v116, v65
	v_sub_u32_e32 v68, 0, v65
	v_max_i32_e32 v68, v65, v68
	v_cvt_f32_u32_e32 v68, v68
	v_cmp_gt_i32_e32 vcc, 0, v65
	s_nop 1
	v_cndmask_b32_e32 v65, v115, v117, vcc
	v_mul_f32_e32 v65, v65, v68
	v_sub_u32_e32 v68, 0, v67
	v_max_i32_e32 v68, v67, v68
	v_cvt_f32_u32_e32 v68, v68
	v_cmp_gt_i32_e32 vcc, 0, v67
	v_exp_f32_e32 v65, v65
	s_nop 0
	v_cndmask_b32_e32 v67, v115, v117, vcc
	v_mul_f32_e32 v67, v67, v68
	v_exp_f32_e32 v67, v67
	v_pk_mul_f32 v[64:65], v[64:65], s[2:3] op_sel_hi:[1,0]
	s_nop 0
	v_pk_mul_f32 v[58:59], v[64:65], v[58:59]
	v_pk_mul_f32 v[64:65], v[66:67], s[2:3] op_sel_hi:[1,0]
	v_or_b32_e32 v67, 0xf9, v114
	v_pk_mul_f32 v[42:43], v[64:65], v[42:43]
	v_or_b32_e32 v64, 0xd8, v114
	v_sub_u32_e32 v64, v116, v64
	v_sub_u32_e32 v66, 0, v64
	v_max_i32_e32 v66, v64, v66
	v_cvt_f32_u32_e32 v66, v66
	v_or_b32_e32 v65, 0xf8, v114
	v_cmp_gt_i32_e32 vcc, 0, v64
	v_sub_u32_e32 v65, v116, v65
	v_sub_u32_e32 v67, v116, v67
	v_cndmask_b32_e32 v64, v115, v117, vcc
	v_mul_f32_e32 v64, v64, v66
	v_sub_u32_e32 v66, 0, v65
	v_max_i32_e32 v66, v65, v66
	v_cvt_f32_u32_e32 v66, v66
	v_cmp_gt_i32_e32 vcc, 0, v65
	v_exp_f32_e32 v64, v64
	s_nop 0
	v_cndmask_b32_e32 v65, v115, v117, vcc
	v_mul_f32_e32 v65, v65, v66
	v_exp_f32_e32 v66, v65
	v_or_b32_e32 v65, 0xd9, v114
	v_sub_u32_e32 v65, v116, v65
	v_sub_u32_e32 v68, 0, v65
	v_max_i32_e32 v68, v65, v68
	v_cvt_f32_u32_e32 v68, v68
	v_cmp_gt_i32_e32 vcc, 0, v65
	s_nop 1
	v_cndmask_b32_e32 v65, v115, v117, vcc
	v_mul_f32_e32 v65, v65, v68
	v_sub_u32_e32 v68, 0, v67
	v_max_i32_e32 v68, v67, v68
	v_cvt_f32_u32_e32 v68, v68
	v_cmp_gt_i32_e32 vcc, 0, v67
	v_exp_f32_e32 v65, v65
	s_nop 0
	v_cndmask_b32_e32 v67, v115, v117, vcc
	v_mul_f32_e32 v67, v67, v68
	v_exp_f32_e32 v67, v67
	v_pk_mul_f32 v[64:65], v[64:65], s[2:3] op_sel_hi:[1,0]
	s_nop 0
	v_pk_mul_f32 v[60:61], v[64:65], v[60:61]
	v_pk_mul_f32 v[64:65], v[66:67], s[2:3] op_sel_hi:[1,0]
	v_or_b32_e32 v67, 0xfb, v114
	v_pk_mul_f32 v[44:45], v[64:65], v[44:45]
	v_or_b32_e32 v64, 0xda, v114
	v_sub_u32_e32 v64, v116, v64
	v_sub_u32_e32 v66, 0, v64
	v_max_i32_e32 v66, v64, v66
	v_cvt_f32_u32_e32 v66, v66
	v_or_b32_e32 v65, 0xfa, v114
	v_cmp_gt_i32_e32 vcc, 0, v64
	v_sub_u32_e32 v65, v116, v65
	v_sub_u32_e32 v67, v116, v67
	v_cndmask_b32_e32 v64, v115, v117, vcc
	v_mul_f32_e32 v64, v64, v66
	v_sub_u32_e32 v66, 0, v65
	v_max_i32_e32 v66, v65, v66
	v_cvt_f32_u32_e32 v66, v66
	v_cmp_gt_i32_e32 vcc, 0, v65
	v_exp_f32_e32 v64, v64
	s_nop 0
	v_cndmask_b32_e32 v65, v115, v117, vcc
	v_mul_f32_e32 v65, v65, v66
	v_exp_f32_e32 v66, v65
	v_or_b32_e32 v65, 0xdb, v114
	v_sub_u32_e32 v65, v116, v65
	v_sub_u32_e32 v68, 0, v65
	v_max_i32_e32 v68, v65, v68
	v_cvt_f32_u32_e32 v68, v68
	v_cmp_gt_i32_e32 vcc, 0, v65
	s_nop 1
	v_cndmask_b32_e32 v65, v115, v117, vcc
	v_mul_f32_e32 v65, v65, v68
	v_sub_u32_e32 v68, 0, v67
	v_max_i32_e32 v68, v67, v68
	v_cvt_f32_u32_e32 v68, v68
	v_cmp_gt_i32_e32 vcc, 0, v67
	v_exp_f32_e32 v65, v65
	s_nop 0
	v_cndmask_b32_e32 v67, v115, v117, vcc
	v_mul_f32_e32 v67, v67, v68
	v_exp_f32_e32 v67, v67
	v_pk_mul_f32 v[64:65], v[64:65], s[2:3] op_sel_hi:[1,0]
	s_nop 0
	v_pk_mul_f32 v[70:71], v[64:65], v[62:63]
	v_pk_mul_f32 v[62:63], v[66:67], s[2:3] op_sel_hi:[1,0]
	s_nop 0
	v_pk_mul_f32 v[46:47], v[62:63], v[46:47]
	ds_read_b128 v[52:55], v74 offset:32256
	ds_read_b128 v[62:65], v74 offset:27648
	ds_read_b128 v[66:69], v74 offset:27680
	s_waitcnt lgkmcnt(2)
	v_mfma_f32_32x32x16_bf16 v[16:31], v[52:55], v[48:51], v[16:31]
	ds_read_b128 v[52:55], v74 offset:32288
	s_waitcnt lgkmcnt(2)
	v_mfma_f32_32x32x16_bf16 v[0:15], v[62:65], v[48:51], v[0:15]
	v_cvt_pk_bf16_f32 v48, v56, v57
	v_cvt_pk_bf16_f32 v49, v58, v59
	v_cvt_pk_bf16_f32 v50, v60, v61
	v_cvt_pk_bf16_f32 v51, v70, v71
	s_waitcnt lgkmcnt(1)
	s_nop 0
	v_mfma_f32_32x32x16_bf16 v[0:15], v[66:69], v[48:51], v[0:15]
	s_waitcnt lgkmcnt(0)
	v_mfma_f32_32x32x16_bf16 v[16:31], v[52:55], v[48:51], v[16:31]
	ds_read_b128 v[36:39], v74 offset:27712
	ds_read_b128 v[48:51], v74 offset:32320
	s_waitcnt lgkmcnt(1)
	v_mfma_f32_32x32x16_bf16 v[0:15], v[36:39], v[32:35], v[0:15]
	s_waitcnt lgkmcnt(0)
	v_mfma_f32_32x32x16_bf16 v[16:31], v[48:51], v[32:35], v[16:31]
	v_cvt_pk_bf16_f32 v32, v40, v41
	v_cvt_pk_bf16_f32 v33, v42, v43
	ds_read_b128 v[36:39], v74 offset:27744
	ds_read_b128 v[40:43], v74 offset:32352
	v_cvt_pk_bf16_f32 v34, v44, v45
	v_cvt_pk_bf16_f32 v35, v46, v47
	s_waitcnt lgkmcnt(0)
	s_barrier
	v_mfma_f32_32x32x16_bf16 v[0:15], v[36:39], v[32:35], v[0:15]
	v_mfma_f32_32x32x16_bf16 v[16:31], v[40:43], v[32:35], v[16:31]
	s_cbranch_scc1 .LBB0_1187
	v_lshlrev_b32_e32 v130, 7, v73
	v_lshl_add_u64 v[32:33], s[4:5], 0, v[130:131]
	v_lshlrev_b32_e32 v130, 1, v72
	v_lshl_add_u64 v[126:127], v[32:33], 0, v[130:131]
	v_add_co_u32_e32 v146, vcc, 0x1000, v126
	global_load_dwordx4 v[32:35], v[126:127], off
	s_nop 0
	v_addc_co_u32_e32 v147, vcc, 0, v127, vcc
	v_add_co_u32_e32 v148, vcc, 0x2000, v126
	global_load_dwordx4 v[36:39], v[146:147], off
	s_nop 0
	v_addc_co_u32_e32 v149, vcc, 0, v127, vcc
	v_add_co_u32_e32 v150, vcc, 0x3000, v126
	global_load_dwordx4 v[48:51], v[148:149], off
	s_nop 0
	v_addc_co_u32_e32 v151, vcc, 0, v127, vcc
	global_load_dwordx4 v[52:55], v[150:151], off
	s_waitcnt vmcnt(3)
	v_mfma_f32_32x32x16_bf16 v[64:79], v[32:35], v[108:111], 0
	s_waitcnt vmcnt(2)
	v_mfma_f32_32x32x16_bf16 v[32:47], v[36:39], v[108:111], 0
	s_waitcnt vmcnt(1)
	v_mfma_f32_32x32x16_bf16 v[80:95], v[48:51], v[108:111], 0
	s_waitcnt vmcnt(0)
	v_mfma_f32_32x32x16_bf16 v[48:63], v[52:55], v[108:111], 0
	global_load_dwordx4 v[108:111], v[126:127], off offset:32
	global_load_dwordx4 v[118:121], v[146:147], off offset:32
	global_load_dwordx4 v[122:125], v[148:149], off offset:32
	global_load_dwordx4 v[142:145], v[150:151], off offset:32
	s_waitcnt vmcnt(3)
	v_mfma_f32_32x32x16_bf16 v[64:79], v[108:111], v[104:107], v[64:79]
	s_waitcnt vmcnt(2)
	v_mfma_f32_32x32x16_bf16 v[32:47], v[118:121], v[104:107], v[32:47]
	s_waitcnt vmcnt(1)
	v_mfma_f32_32x32x16_bf16 v[80:95], v[122:125], v[104:107], v[80:95]
	s_waitcnt vmcnt(0)
	v_mfma_f32_32x32x16_bf16 v[48:63], v[142:145], v[104:107], v[48:63]
	global_load_dwordx4 v[104:107], v[126:127], off offset:64
	global_load_dwordx4 v[108:111], v[146:147], off offset:64
	global_load_dwordx4 v[118:121], v[148:149], off offset:64
	global_load_dwordx4 v[122:125], v[150:151], off offset:64
	s_waitcnt vmcnt(3)
	v_mfma_f32_32x32x16_bf16 v[64:79], v[104:107], v[100:103], v[64:79]
	s_waitcnt vmcnt(2)
	v_mfma_f32_32x32x16_bf16 v[32:47], v[108:111], v[100:103], v[32:47]
	s_waitcnt vmcnt(1)
	v_mfma_f32_32x32x16_bf16 v[80:95], v[118:121], v[100:103], v[80:95]
	s_waitcnt vmcnt(0)
	v_mfma_f32_32x32x16_bf16 v[48:63], v[122:125], v[100:103], v[48:63]
	global_load_dwordx4 v[100:103], v[126:127], off offset:96
	global_load_dwordx4 v[104:107], v[146:147], off offset:96
	global_load_dwordx4 v[108:111], v[148:149], off offset:96
	global_load_dwordx4 v[118:121], v[150:151], off offset:96
	s_waitcnt vmcnt(3)
	v_mfma_f32_32x32x16_bf16 v[64:79], v[100:103], v[96:99], v[64:79]
	s_waitcnt vmcnt(2)
	v_mfma_f32_32x32x16_bf16 v[32:47], v[104:107], v[96:99], v[32:47]
	s_waitcnt vmcnt(1)
	v_mfma_f32_32x32x16_bf16 v[80:95], v[108:111], v[96:99], v[80:95]
	s_waitcnt vmcnt(0)
	v_mfma_f32_32x32x16_bf16 v[48:63], v[118:121], v[96:99], v[48:63]
	v_sub_u32_e32 v97, 0x100, v116
	v_add_u32_e32 v96, 1, v116
	v_cvt_f32_i32_e32 v97, v97
	v_cvt_f32_i32_e32 v96, v96
	v_mul_f32_e32 v97, v117, v97
	v_mul_f32_e32 v96, v115, v96
	v_exp_f32_e32 v98, v97
	v_exp_f32_e32 v96, v96
	s_nop 3
	v_pk_mul_f32 v[48:49], v[98:99], v[48:49] op_sel_hi:[0,1]
	v_pk_fma_f32 v[32:33], v[96:97], v[32:33], v[48:49] op_sel_hi:[0,1,1]
	v_pk_add_f32 v[16:17], v[16:17], v[32:33]
	v_pk_mul_f32 v[32:33], v[98:99], v[82:83] op_sel_hi:[0,1]
	v_pk_fma_f32 v[32:33], v[96:97], v[66:67], v[32:33] op_sel_hi:[0,1,1]
	v_pk_add_f32 v[2:3], v[2:3], v[32:33]
	v_pk_mul_f32 v[32:33], v[98:99], v[50:51] op_sel_hi:[0,1]
	v_pk_fma_f32 v[32:33], v[96:97], v[34:35], v[32:33] op_sel_hi:[0,1,1]
	v_pk_add_f32 v[18:19], v[18:19], v[32:33]
	v_pk_mul_f32 v[32:33], v[98:99], v[84:85] op_sel_hi:[0,1]
	v_pk_fma_f32 v[32:33], v[96:97], v[68:69], v[32:33] op_sel_hi:[0,1,1]
	v_pk_add_f32 v[4:5], v[4:5], v[32:33]
	v_pk_mul_f32 v[32:33], v[98:99], v[52:53] op_sel_hi:[0,1]
	v_pk_fma_f32 v[32:33], v[96:97], v[36:37], v[32:33] op_sel_hi:[0,1,1]
	v_pk_add_f32 v[20:21], v[20:21], v[32:33]
	v_pk_mul_f32 v[32:33], v[98:99], v[86:87] op_sel_hi:[0,1]
	v_pk_fma_f32 v[32:33], v[96:97], v[70:71], v[32:33] op_sel_hi:[0,1,1]
	v_pk_add_f32 v[6:7], v[6:7], v[32:33]
	v_pk_mul_f32 v[32:33], v[98:99], v[54:55] op_sel_hi:[0,1]
	v_pk_fma_f32 v[32:33], v[96:97], v[38:39], v[32:33] op_sel_hi:[0,1,1]
	v_pk_add_f32 v[22:23], v[22:23], v[32:33]
	v_pk_mul_f32 v[32:33], v[98:99], v[88:89] op_sel_hi:[0,1]
	v_pk_fma_f32 v[32:33], v[96:97], v[72:73], v[32:33] op_sel_hi:[0,1,1]
	v_pk_add_f32 v[8:9], v[8:9], v[32:33]
	v_pk_mul_f32 v[32:33], v[98:99], v[56:57] op_sel_hi:[0,1]
	v_pk_fma_f32 v[32:33], v[96:97], v[40:41], v[32:33] op_sel_hi:[0,1,1]
	v_pk_add_f32 v[24:25], v[24:25], v[32:33]
	v_pk_mul_f32 v[32:33], v[98:99], v[90:91] op_sel_hi:[0,1]
	v_pk_fma_f32 v[32:33], v[96:97], v[74:75], v[32:33] op_sel_hi:[0,1,1]
	v_pk_add_f32 v[10:11], v[10:11], v[32:33]
	v_pk_mul_f32 v[32:33], v[98:99], v[58:59] op_sel_hi:[0,1]
	v_pk_fma_f32 v[32:33], v[96:97], v[42:43], v[32:33] op_sel_hi:[0,1,1]
	v_pk_add_f32 v[26:27], v[26:27], v[32:33]
	v_pk_mul_f32 v[32:33], v[98:99], v[92:93] op_sel_hi:[0,1]
	v_pk_fma_f32 v[32:33], v[96:97], v[76:77], v[32:33] op_sel_hi:[0,1,1]
	v_pk_mul_f32 v[80:81], v[98:99], v[80:81] op_sel_hi:[0,1]
	v_pk_add_f32 v[12:13], v[12:13], v[32:33]
	v_pk_mul_f32 v[32:33], v[98:99], v[60:61] op_sel_hi:[0,1]
	v_pk_fma_f32 v[64:65], v[96:97], v[64:65], v[80:81] op_sel_hi:[0,1,1]
	v_pk_fma_f32 v[32:33], v[96:97], v[44:45], v[32:33] op_sel_hi:[0,1,1]
	v_mul_f32_e32 v34, v98, v94
	v_mov_b32_e32 v97, v98
	v_mov_b32_e32 v94, v79
	v_pk_mul_f32 v[40:41], v[96:97], v[94:95]
	v_pk_add_f32 v[28:29], v[28:29], v[32:33]
	v_mul_f32_e32 v32, v96, v78
	v_mov_b32_e32 v33, v40
	v_mov_b32_e32 v35, v41
	v_mul_f32_e32 v38, v98, v62
	v_pk_add_f32 v[32:33], v[32:33], v[34:35]
	v_mov_b32_e32 v62, v47
	v_pk_add_f32 v[14:15], v[14:15], v[32:33]
	v_pk_mul_f32 v[32:33], v[96:97], v[62:63]
	v_mul_f32_e32 v36, v96, v46
	v_mov_b32_e32 v37, v32
	v_mov_b32_e32 v39, v33
	v_pk_add_f32 v[32:33], v[36:37], v[38:39]
	v_pk_add_f32 v[0:1], v[0:1], v[64:65]
	v_pk_add_f32 v[30:31], v[30:31], v[32:33]
